# v12 + layer-0 in-proj GEMM on all 256 workgroups (3 rounds); background weight conversion moved into layer-0 attention phase: workgroups 192..255 convert first then join the attention queue, the rest
# speedup vs baseline: 1.0232x; 1.0029x over previous
.LBB0_20:
	v_readlane_b32 s14, v253, 1
	v_readlane_b32 s15, v253, 2
	s_add_u32 s0, s14, 0xa8
	s_addc_u32 s1, s15, 0
	v_writelane_b32 v253, s0, 11
	s_load_dwordx16 s[36:51], s[14:15], 0x40
	v_mov_b32_e32 v129, 0
	v_writelane_b32 v253, s1, 12
	v_mov_b32_e32 v232, 1
	v_readlane_b32 s1, v253, 0
	s_cmpk_lt_i32 s1, 0x100
	s_cselect_b64 s[2:3], -1, 0
	v_writelane_b32 v253, s2, 13
	s_ashr_i32 s0, s1, 31
	v_mov_b32_e32 v233, 0x260
	v_writelane_b32 v253, s3, 14
	v_writelane_b32 v253, s0, 15
	s_lshr_b32 s0, s0, 29
	s_add_i32 s0, s1, s0
	s_ashr_i32 s2, s0, 3
	s_and_b32 s0, s0, -8
	s_sub_i32 s3, s1, s0
	s_lshl_b32 s5, s3, 5
	s_cmpk_lt_i32 s1, 0x400
	s_cselect_b64 s[6:7], -1, 0
	v_writelane_b32 v253, s6, 16
	v_mov_b64_e32 v[234:235], 0x100
	v_mov_b64_e32 v[236:237], 0xff
	v_writelane_b32 v253, s7, 17
	s_lshl_b32 s6, s3, 7
	v_readlane_b32 s8, v253, 3
	v_readlane_b32 s9, v253, 4
	s_add_u32 s10, s8, 0x8200000
	s_addc_u32 s11, s9, 0
	v_writelane_b32 v253, s10, 18
	s_mov_b32 s7, 0xc0000
	v_mov_b32_e32 v238, 0x42800000
	v_writelane_b32 v253, s11, 19
	s_add_u32 s10, s8, 0x4200000
	s_addc_u32 s11, s9, 0
	v_writelane_b32 v253, s10, 20
	v_mov_b32_e32 v252, 0xff800000
	v_mov_b32_e32 v248, 0xc0000
	v_writelane_b32 v253, s11, 21
	s_add_u32 s10, s8, 0x3200000
	s_addc_u32 s11, s9, 0
	s_add_u32 s30, s8, 0x200000
	s_addc_u32 s31, s9, 0
	v_writelane_b32 v253, s10, 22
	s_cmpk_lt_i32 s1, 0x300
	v_mov_b32_e32 v239, 6
	v_writelane_b32 v253, s11, 23
	s_cselect_b64 s[10:11], -1, 0
	v_writelane_b32 v253, s10, 24
	s_lshl_b32 s0, s1, 3
	v_mov_b32_e32 v240, 4
	v_writelane_b32 v253, s11, 25
	s_add_u32 s10, s8, 0xc400000
	s_addc_u32 s11, s9, 0
	s_add_u32 s78, s8, 0xc200000
	v_writelane_b32 v253, s0, 26
	s_addc_u32 s79, s9, 0
	v_writelane_b32 v253, s10, 27
	s_add_u32 s8, s8, 0xc300000
	s_addc_u32 s9, s9, 0
	v_writelane_b32 v253, s11, 28
	v_writelane_b32 v253, s8, 29
	v_mov_b32_e32 v242, 12
	s_movk_i32 s33, 0x201
	v_writelane_b32 v253, s9, 30
	s_lshl_b32 s8, s1, 9
	s_cmpk_lt_u32 s1, 0x80
	s_cselect_b64 s[0:1], -1, 0
	v_writelane_b32 v253, s0, 31
	s_movk_i32 s80, 0x6020
	s_mov_b64 s[34:35], 0x80
	v_writelane_b32 v253, s1, 32
	s_and_b64 s[0:1], s[0:1], exec
	s_cselect_b32 s0, s7, 0x200000
	v_writelane_b32 v253, s0, 33
	s_and_b32 s0, s8, 0xfe00
	v_writelane_b32 v253, s8, 34
	s_cmp_eq_u32 s4, 15
	v_writelane_b32 v253, s0, 35
	s_cselect_b64 s[0:1], -1, 0
	v_writelane_b32 v253, s0, 36
	s_cmp_eq_u32 s4, 14
	s_mov_b64 s[82:83], 0x600000
	v_writelane_b32 v253, s1, 37
	s_cselect_b64 s[0:1], -1, 0
	v_writelane_b32 v253, s0, 38
	s_cmp_eq_u32 s4, 13
	s_nop 0
	v_writelane_b32 v253, s1, 39
	s_cselect_b64 s[0:1], -1, 0
	v_writelane_b32 v253, s0, 40
	s_cmp_eq_u32 s4, 12
	s_nop 0
	v_writelane_b32 v253, s1, 41
	s_cselect_b64 s[0:1], -1, 0
	v_writelane_b32 v253, s0, 42
	s_cmp_eq_u32 s4, 11
	s_nop 0
	v_writelane_b32 v253, s1, 43
	s_cselect_b64 s[0:1], -1, 0
	v_writelane_b32 v253, s0, 44
	s_cmp_eq_u32 s4, 10
	s_nop 0
	v_writelane_b32 v253, s1, 45
	s_cselect_b64 s[0:1], -1, 0
	v_writelane_b32 v253, s0, 46
	s_cmp_eq_u32 s4, 9
	s_nop 0
	v_writelane_b32 v253, s1, 47
	s_cselect_b64 s[0:1], -1, 0
	v_writelane_b32 v253, s0, 48
	s_cmp_eq_u32 s4, 8
	s_nop 0
	v_writelane_b32 v253, s1, 49
	s_cselect_b64 s[0:1], -1, 0
	v_writelane_b32 v253, s0, 50
	s_cmp_eq_u32 s4, 7
	s_nop 0
	v_writelane_b32 v253, s1, 51
	s_cselect_b64 s[0:1], -1, 0
	v_writelane_b32 v253, s0, 52
	s_cmp_eq_u32 s4, 6
	s_nop 0
	v_writelane_b32 v253, s1, 53
	s_cselect_b64 s[0:1], -1, 0
	v_writelane_b32 v253, s0, 54
	s_cmp_eq_u32 s4, 5
	s_nop 0
	v_writelane_b32 v253, s1, 55
	s_cselect_b64 s[0:1], -1, 0
	v_writelane_b32 v253, s0, 56
	s_cmp_eq_u32 s4, 4
	s_nop 0
	v_writelane_b32 v253, s1, 57
	s_cselect_b64 s[0:1], -1, 0
	v_writelane_b32 v253, s0, 58
	s_cmp_eq_u32 s4, 3
	s_nop 0
	v_writelane_b32 v253, s1, 59
	s_cselect_b64 s[0:1], -1, 0
	v_writelane_b32 v253, s0, 60
	s_cmp_eq_u32 s4, 2
	s_nop 0
	v_writelane_b32 v253, s1, 61
	s_cselect_b64 s[0:1], -1, 0
	v_writelane_b32 v253, s0, 62
	s_cmp_eq_u32 s4, 1
	s_nop 0
	v_writelane_b32 v253, s1, 63
	s_cselect_b64 s[0:1], -1, 0
	v_writelane_b32 v254, s0, 0
	s_cmp_eq_u32 s4, 0
	s_nop 0
	v_writelane_b32 v254, s1, 1
	s_cselect_b64 s[0:1], -1, 0
	v_writelane_b32 v254, s0, 2
	s_nop 1
	v_writelane_b32 v254, s1, 3
	s_lshl_b32 s0, s4, 6
	s_cmp_lt_i32 s3, 0
	s_mul_i32 s1, s3, 33
	s_mul_i32 s4, s3, 0x81
	s_cselect_b32 s1, s1, s5
	s_movk_i32 s5, 0x61
	s_cselect_b32 s4, s4, s6
	s_cselect_b32 s5, s5, 0x60
	s_add_i32 s1, s1, s2
	s_ashr_i32 s6, s1, 31
	s_lshr_b32 s6, s6, 27
	s_add_i32 s6, s1, s6
	s_and_b32 s7, s6, 0xffe0
	s_sub_i32 s1, s1, s7
	s_bfe_i32 s7, s1, 0x80000
	s_bfe_u32 s7, s7, 0x2000d
	s_add_i32 s7, s1, s7
	s_and_b32 s8, s7, 0xfc
	s_add_i32 s4, s4, s2
	s_sub_i32 s1, s1, s8
	s_ashr_i32 s8, s4, 31
	s_lshr_b32 s8, s8, 26
	s_add_i32 s8, s4, s8
	s_and_b32 s9, s8, 0xffc0
	s_sub_i32 s4, s4, s9
	s_mul_i32 s3, s3, s5
	s_bfe_u32 s9, s4, 0x10007
	s_add_i32 s3, s3, s2
	s_add_i32 s9, s4, s9
	s_mul_hi_i32 s2, s3, 0x2aaaaaab
	s_and_b32 s10, s9, 0xfe
	s_lshr_b32 s5, s2, 31
	s_ashr_i32 s2, s2, 4
	s_sub_i32 s4, s4, s10
	s_add_i32 s10, s2, s5
	s_mul_i32 s2, s10, 0x60
	s_sub_i32 s2, s3, s2
	s_ashr_i32 s3, s6, 5
	s_lshl_b32 s3, s3, 2
	s_sext_i32_i8 s1, s1
	s_add_i32 s12, s3, s1
	s_bfe_i32 s1, s2, 0x80000
	s_bfe_u32 s1, s1, 0x2000d
	s_bfe_i32 s5, s7, 0x80000
	s_add_i32 s1, s2, s1
	s_sext_i32_i16 s5, s5
	s_and_b32 s3, s1, 0xfc
	s_sub_i32 s6, s2, s3
	s_ashr_i32 s2, s5, 2
	v_writelane_b32 v254, s2, 4
	s_lshr_b32 s2, s5, 2
	s_ashr_i32 s5, s8, 6
	s_bfe_i32 s7, s9, 0x80000
	s_lshl_b32 s5, s5, 1
	s_sext_i32_i16 s7, s7
	s_sext_i32_i8 s4, s4
	s_add_i32 s8, s5, s4
	s_ashr_i32 s4, s7, 1
	v_writelane_b32 v254, s4, 5
	s_lshr_b32 s4, s7, 1
	s_bfe_i64 s[4:5], s[4:5], 0x100000
	s_lshl_b64 s[4:5], s[4:5], 20
	s_bfe_i64 s[2:3], s[2:3], 0x100000
	v_writelane_b32 v254, s4, 6
	s_bfe_i32 s1, s1, 0x80000
	s_sext_i32_i16 s1, s1
	v_writelane_b32 v254, s5, 7
	s_lshl_b64 s[4:5], s[2:3], 22
	v_writelane_b32 v254, s4, 8
	s_lshl_b64 s[2:3], s[2:3], 20
	s_lshl_b32 s0, s0, 2
	v_writelane_b32 v254, s5, 9
	v_writelane_b32 v254, s2, 10
	s_ashr_i32 s13, s12, 31
	s_ashr_i32 s9, s8, 31
	v_writelane_b32 v254, s3, 11
	s_lshl_b32 s2, s10, 2
	s_sext_i32_i8 s3, s6
	s_add_i32 s4, s2, s3
	s_ashr_i32 s2, s1, 2
	v_writelane_b32 v254, s2, 12
	s_lshr_b32 s2, s1, 2
	s_bfe_i64 s[2:3], s[2:3], 0x100000
	s_lshl_b64 s[2:3], s[2:3], 20
	v_writelane_b32 v254, s2, 13
	s_mov_b32 s1, 0
	s_ashr_i32 s5, s4, 31
	v_writelane_b32 v254, s3, 14
	v_writelane_b32 v254, s0, 15
	s_add_i32 s0, 0, 0x222e0
	v_writelane_b32 v254, s0, 16
	s_add_i32 s0, 0, 0x23fc0
	v_writelane_b32 v254, s0, 17
	s_add_i32 s0, 0, 0x23fc4
	v_writelane_b32 v254, s0, 18
	v_writelane_b32 v254, s0, 19
	s_movk_i32 s3, 0x81
	s_mov_b32 s2, 0xff800000
	v_writelane_b32 v254, s1, 20
	s_lshl_b64 s[0:1], s[12:13], 22
	v_writelane_b32 v254, s0, 21
	s_nop 1
	v_writelane_b32 v254, s1, 22
	s_mov_b32 s0, s8
	v_writelane_b32 v254, s0, 23
	s_nop 1
	v_writelane_b32 v254, s1, 24
	s_lshl_b64 s[0:1], s[8:9], 20
	v_writelane_b32 v254, s0, 25
	s_nop 1
	v_writelane_b32 v254, s1, 26
	s_mov_b32 s0, s12
	v_writelane_b32 v254, s0, 27
	s_nop 1
	v_writelane_b32 v254, s1, 28
	s_lshl_b64 s[0:1], s[12:13], 20
	v_writelane_b32 v254, s0, 29
	s_mov_b64 s[12:13], 0x100
	s_nop 0
	v_writelane_b32 v254, s1, 30
	s_mov_b32 s0, s4
	v_writelane_b32 v254, s0, 31
	s_nop 1
	v_writelane_b32 v254, s1, 32
	s_lshl_b64 s[0:1], s[4:5], 20
	v_writelane_b32 v254, s0, 33
	s_nop 1
	v_writelane_b32 v254, s1, 34
	s_waitcnt lgkmcnt(0)
	v_writelane_b32 v254, s36, 35
	s_nop 1
	v_writelane_b32 v254, s37, 36
	v_writelane_b32 v254, s38, 37
	v_writelane_b32 v254, s39, 38
	v_writelane_b32 v254, s40, 39
	v_writelane_b32 v254, s41, 40
	v_writelane_b32 v254, s42, 41
	v_writelane_b32 v254, s43, 42
	v_writelane_b32 v254, s44, 43
	v_writelane_b32 v254, s45, 44
	v_writelane_b32 v254, s46, 45
	v_writelane_b32 v254, s47, 46
	v_writelane_b32 v254, s48, 47
	v_writelane_b32 v254, s49, 48
	v_writelane_b32 v254, s50, 49
	v_writelane_b32 v254, s51, 50
	s_load_dwordx16 s[36:51], s[14:15], 0x0
	s_waitcnt lgkmcnt(0)
	v_writelane_b32 v254, s36, 51
	s_nop 1
	v_writelane_b32 v254, s37, 52
	v_writelane_b32 v254, s38, 53
	v_writelane_b32 v254, s39, 54
	v_writelane_b32 v254, s40, 55
	v_writelane_b32 v254, s41, 56
	v_writelane_b32 v254, s42, 57
	v_writelane_b32 v255, s49, 0
	v_writelane_b32 v254, s43, 58
	v_writelane_b32 v255, s50, 1
	v_writelane_b32 v254, s44, 59
	v_writelane_b32 v255, s51, 2
	v_writelane_b32 v254, s45, 60
	v_writelane_b32 v255, s30, 3
	v_writelane_b32 v254, s46, 61
	v_writelane_b32 v254, s47, 62
	v_writelane_b32 v255, s31, 4
	v_writelane_b32 v255, s78, 5
	v_writelane_b32 v254, s48, 63
	s_nop 0
	v_writelane_b32 v255, s79, 6
	s_mov_b32 s98, 0
	v_writelane_b32 v255, s98, 62
	s_branch .LBB0_24

.Lattn_setup:
	s_add_u32 s0, s22, 0xc300000
	v_writelane_b32 v255, s0, 18
	s_addc_u32 s0, s23, 0
	v_writelane_b32 v255, s0, 19
	v_readlane_b32 s36, v254, 51
	v_readlane_b32 s0, v255, 7
	v_readlane_b32 s1, v255, 8
	s_mov_b32 s8, s0
	s_lshl_b32 s0, s0, 3
	s_ashr_i32 s1, s0, 31
	s_lshl_b64 s[0:1], s[0:1], 2
	v_readlane_b32 s40, v254, 55
	v_readlane_b32 s41, v254, 56
	s_add_u32 s0, s40, s0
	s_addc_u32 s1, s41, s1
	v_readlane_b32 s49, v255, 0
	v_readlane_b32 s50, v255, 1
	v_readlane_b32 s51, v255, 2
	v_writelane_b32 v255, s0, 20
	v_readlane_b32 s42, v254, 57
	v_readlane_b32 s43, v254, 58
	v_writelane_b32 v255, s1, 21
	s_lshl_b32 s0, s8, 6
	s_ashr_i32 s1, s0, 31
	s_lshl_b64 s[4:5], s[0:1], 2
	s_add_u32 s0, s42, s4
	s_addc_u32 s1, s43, s5
	v_readlane_b32 s44, v254, 59
	v_writelane_b32 v255, s0, 22
	v_readlane_b32 s45, v254, 60
	v_readlane_b32 s46, v254, 61
	v_writelane_b32 v255, s1, 23
	s_add_u32 s0, s44, s4
	s_addc_u32 s1, s45, s5
	v_writelane_b32 v255, s0, 24
	v_readlane_b32 s47, v254, 62
	v_readlane_b32 s48, v254, 63
	v_writelane_b32 v255, s1, 25
	s_add_u32 s0, s46, s4
	s_addc_u32 s1, s47, s5
	v_writelane_b32 v255, s0, 26
	s_mov_b32 s6, s8
	v_readlane_b32 s37, v254, 52
	v_writelane_b32 v255, s1, 27
	s_add_u32 s0, s48, s4
	s_addc_u32 s1, s49, s5
	v_writelane_b32 v255, s0, 28
	v_readlane_b32 s38, v254, 53
	v_readlane_b32 s39, v254, 54
	v_writelane_b32 v255, s1, 29
	s_lshl_b32 s0, s8, 7
	s_ashr_i32 s1, s0, 31
	s_lshl_b64 s[0:1], s[0:1], 2
	s_add_u32 s0, s50, s0
	s_addc_u32 s1, s51, s1
	s_ashr_i32 s9, s8, 31
	v_writelane_b32 v255, s6, 7
	s_nop 1
	v_writelane_b32 v255, s7, 8
	s_lshl_b64 s[6:7], s[8:9], 2
	v_readlane_b32 s8, v253, 1
	v_readlane_b32 s9, v253, 2
	s_add_u32 s6, s8, s6
	s_addc_u32 s7, s9, s7
	s_load_dword s8, s[6:7], 0x98
	s_add_u32 s4, s22, s4
	s_load_dword s6, s[6:7], 0xa0
	s_addc_u32 s5, s23, s5
	s_waitcnt lgkmcnt(0)
	v_writelane_b32 v255, s8, 30
	v_writelane_b32 v255, s6, 31
	v_writelane_b32 v255, s4, 32
	s_nop 1
	v_writelane_b32 v255, s5, 33
	s_add_u32 s4, s22, 0x12401c70
	v_writelane_b32 v255, s4, 34
	s_addc_u32 s4, s23, 0
	v_writelane_b32 v255, s4, 35
	s_add_u32 s4, s22, 0x12401cf0
	v_writelane_b32 v255, s4, 36
	s_addc_u32 s4, s23, 0
	v_writelane_b32 v255, s4, 37
	v_readlane_b32 s4, v253, 9
	s_cmp_eq_u32 s4, 2
	s_cbranch_scc0 .Lattn_go
	v_readlane_b32 s4, v253, 0
	s_cmpk_lt_u32 s4, 0xc0
	s_cbranch_scc1 .Lattn_go
	v_readlane_b32 s4, v255, 62
	s_cmp_eq_u32 s4, 0
	s_cbranch_scc0 .Lattn_go
	s_mov_b32 s4, 1
	v_writelane_b32 v255, s4, 62
	s_branch .LBB0_480
.Lattn_go:
	s_branch .LBB0_173

.LBB0_487:
	s_or_b64 exec, exec, s[0:1]
	v_readlane_b32 s0, v254, 16
	s_waitcnt lgkmcnt(0)
	s_barrier
	s_waitcnt vmcnt(23)
	v_mov_b32_e32 v0, s0
	ds_read_b32 v0, v0
	s_movk_i32 s0, 0x29f
	s_waitcnt lgkmcnt(0)
	s_barrier
	v_cmp_lt_i32_e32 vcc, s0, v0
	s_mov_b64 s[0:1], -1
	s_cbranch_vccnz .LBB0_484
	v_lshlrev_b32_e32 v0, 5, v0
	v_add_u32_e32 v1, 0xc00, v0
	v_add_u32_e32 v133, 0xc20, v0
	v_add_u32_e32 v154, v1, v131
	v_cmp_lt_i32_e32 vcc, v154, v133
	s_mov_b32 s0, 0x2aaaaaab
	v_mov_b32_e32 v36, v241
	v_cndmask_b32_e32 v0, v1, v154, vcc
	v_mul_hi_i32 v1, v0, s0
	v_lshrrev_b32_e32 v2, 31, v1
	v_ashrrev_i32_e32 v1, 11, v1
	s_waitcnt vmcnt(22)
	v_add_u32_e32 v4, v1, v2
	v_mul_i32_i24_e32 v1, 0x3000, v4
	s_waitcnt vmcnt(21)
	v_sub_u32_e32 v8, v0, v1
	s_movk_i32 s0, 0xbff
	v_cmp_lt_i32_e64 s[4:5], s0, v8
	s_and_saveexec_b64 s[0:1], s[4:5]
	s_xor_b64 s[0:1], exec, s[0:1]
	s_cbranch_execz .LBB0_499
	s_movk_i32 s4, 0xfff
	v_cmp_lt_u32_e64 s[4:5], s4, v8
	v_ashrrev_i32_e32 v5, 31, v4
	s_and_saveexec_b64 s[6:7], s[4:5]
	s_xor_b64 s[6:7], exec, s[6:7]
	s_cbranch_execz .LBB0_495
	s_movk_i32 s4, 0x1fff
	v_cmp_lt_u32_e64 s[4:5], s4, v8
	v_lshlrev_b64 v[6:7], 26, v[4:5]
	v_lshlrev_b32_e32 v10, 6, v8
	v_lshlrev_b64 v[4:5], 25, v[4:5]
	s_and_saveexec_b64 s[8:9], s[4:5]
	s_xor_b64 s[4:5], exec, s[8:9]
	s_cbranch_execz .LBB0_492
	v_add_u32_e32 v0, 0xffffe000, v8
	v_lshrrev_b32_e32 v8, 5, v0
	v_readlane_b32 s40, v254, 35
	v_readlane_b32 s48, v254, 43
	v_readlane_b32 s49, v254, 44
	v_lshlrev_b32_e32 v128, 6, v8
	v_lshlrev_b64 v[2:3], 13, v[128:129]
	v_lshl_add_u64 v[0:1], s[48:49], 0, v[6:7]
	v_lshl_add_u64 v[0:1], v[0:1], 0, v[2:3]
	v_and_b32_e32 v2, 0x7c0, v10
	v_lshlrev_b32_e32 v128, 2, v2
	v_readlane_b32 s8, v253, 18
	v_and_b32_e32 v3, 0x780, v10
	v_lshl_add_u64 v[32:33], v[0:1], 0, v[128:129]
	v_readlane_b32 s9, v253, 19
	v_add_u32_e32 v128, v3, v8
	v_readlane_b32 s41, v254, 36
	v_readlane_b32 s42, v254, 37
	v_readlane_b32 s43, v254, 38
	v_readlane_b32 s44, v254, 39
	v_readlane_b32 s45, v254, 40
	v_readlane_b32 s46, v254, 41
	v_readlane_b32 s47, v254, 42
	v_readlane_b32 s50, v254, 45
	v_readlane_b32 s51, v254, 46
	v_readlane_b32 s52, v254, 47
	v_readlane_b32 s53, v254, 48
	v_readlane_b32 s54, v254, 49
	v_readlane_b32 s55, v254, 50
	v_lshl_add_u64 v[0:1], s[8:9], 0, v[4:5]
	v_lshlrev_b32_e32 v9, 6, v2
	v_mov_b64_e32 v[2:3], v[128:129]

.LBB0_533:
	v_readlane_b32 s4, v255, 62
	s_cmp_eq_u32 s4, 1
	s_cbranch_scc0 .Lconv_done
	s_mov_b32 s4, 2
	v_writelane_b32 v255, s4, 62
	v_readlane_b32 s22, v253, 3
	v_readlane_b32 s23, v253, 4
	s_branch .Lattn_setup

.LBB0_534:
	s_and_b64 vcc, exec, s[0:1]
	s_cbranch_vccz .LBB0_650
	v_readlane_b32 s0, v255, 15
	s_cmp_lg_u32 s0, 0
	s_cbranch_scc1 .LBB0_650
	v_readlane_b32 s0, v253, 9
	v_readlane_b32 s1, v253, 10
	s_add_i32 s0, s0, 3
	s_cmp_gt_u32 s0, 8
	s_mov_b64 s[0:1], 0
	s_cbranch_scc1 .LBB0_538
	v_readlane_b32 s0, v253, 11
	v_readlane_b32 s1, v253, 12
	s_load_dword s0, s[0:1], 0x0
	s_waitcnt lgkmcnt(0)
	s_cmpk_gt_i32 s0, 0xc0
	s_mov_b64 s[0:1], 0
